# v99 plus prologue residual-stream copy with eight 16-byte loads per thread in flight (was one load then a full wait, 33 times)
# speedup vs baseline: 1.0117x; 1.0018x over previous
; __device__ __forceinline__ void p0_prologue(const Frame& F) {
;     ...
;         f32x4* X = (f32x4*)(ws + WS_X);
;         const f32x4* x = (const f32x4*)F.in[I_X]; const f32x4* cx = (const f32x4*)F.in[I_CTX];
;         const size_t n1 = (size_t)SEQ * D / 4, n2 = (size_t)CTXL * D / 4;
;         for (size_t i = (size_t)F.bid * NTHREADS + F.tid; i < n1 + n2; i += (size_t)F.nb * NTHREADS) X[i] = (i < n1) ? x[i] : cx[i - n1];
.LBB0_119:
	s_mov_b64 s[24:25], 0
	s_mov_b64 s[26:27], 0
	s_mov_b64 s[28:29], 0
	s_mov_b64 s[30:31], 0
	s_mov_b64 s[32:33], 0
	s_mov_b64 s[34:35], 0
	s_mov_b64 s[38:39], 0
	s_mov_b64 s[42:43], 0
	s_mov_b64 s[24:25], exec
	v_cmp_gt_u64_e32 vcc, s[14:15], v[4:5]
	v_lshl_add_u64 v[118:119], s[36:37], 0, v[2:3]
	v_lshl_add_u64 v[120:121], s[8:9], 0, v[2:3]
	v_lshl_add_u64 v[102:103], s[4:5], 0, v[2:3]
	v_cndmask_b32_e32 v119, v121, v119, vcc
	v_cndmask_b32_e32 v118, v120, v118, vcc
	v_lshl_add_u64 v[4:5], v[4:5], 0, s[6:7]
	global_load_dwordx4 v[70:73], v[118:119], off
	v_lshl_add_u64 v[2:3], v[2:3], 0, s[10:11]
	v_cmp_ge_u64_e32 vcc, s[16:17], v[4:5]
	s_and_b64 exec, exec, vcc
	s_cbranch_execz .Lmy_xc_ld_done
	s_mov_b64 s[26:27], exec
	v_cmp_gt_u64_e32 vcc, s[14:15], v[4:5]
	v_lshl_add_u64 v[118:119], s[36:37], 0, v[2:3]
	v_lshl_add_u64 v[120:121], s[8:9], 0, v[2:3]
	v_lshl_add_u64 v[104:105], s[4:5], 0, v[2:3]
	v_cndmask_b32_e32 v119, v121, v119, vcc
	v_cndmask_b32_e32 v118, v120, v118, vcc
	v_lshl_add_u64 v[4:5], v[4:5], 0, s[6:7]
	global_load_dwordx4 v[74:77], v[118:119], off
	v_lshl_add_u64 v[2:3], v[2:3], 0, s[10:11]
	v_cmp_ge_u64_e32 vcc, s[16:17], v[4:5]
	s_and_b64 exec, exec, vcc
	s_cbranch_execz .Lmy_xc_ld_done
	s_mov_b64 s[28:29], exec
	v_cmp_gt_u64_e32 vcc, s[14:15], v[4:5]
	v_lshl_add_u64 v[118:119], s[36:37], 0, v[2:3]
	v_lshl_add_u64 v[120:121], s[8:9], 0, v[2:3]
	v_lshl_add_u64 v[106:107], s[4:5], 0, v[2:3]
	v_cndmask_b32_e32 v119, v121, v119, vcc
	v_cndmask_b32_e32 v118, v120, v118, vcc
	v_lshl_add_u64 v[4:5], v[4:5], 0, s[6:7]
	global_load_dwordx4 v[78:81], v[118:119], off
	v_lshl_add_u64 v[2:3], v[2:3], 0, s[10:11]
	v_cmp_ge_u64_e32 vcc, s[16:17], v[4:5]
	s_and_b64 exec, exec, vcc
	s_cbranch_execz .Lmy_xc_ld_done
	s_mov_b64 s[30:31], exec
	v_cmp_gt_u64_e32 vcc, s[14:15], v[4:5]
	v_lshl_add_u64 v[118:119], s[36:37], 0, v[2:3]
	v_lshl_add_u64 v[120:121], s[8:9], 0, v[2:3]
	v_lshl_add_u64 v[108:109], s[4:5], 0, v[2:3]
	v_cndmask_b32_e32 v119, v121, v119, vcc
	v_cndmask_b32_e32 v118, v120, v118, vcc
	v_lshl_add_u64 v[4:5], v[4:5], 0, s[6:7]
	global_load_dwordx4 v[82:85], v[118:119], off
	v_lshl_add_u64 v[2:3], v[2:3], 0, s[10:11]
	v_cmp_ge_u64_e32 vcc, s[16:17], v[4:5]
	s_and_b64 exec, exec, vcc
	s_cbranch_execz .Lmy_xc_ld_done
	s_mov_b64 s[32:33], exec
	v_cmp_gt_u64_e32 vcc, s[14:15], v[4:5]
	v_lshl_add_u64 v[118:119], s[36:37], 0, v[2:3]
	v_lshl_add_u64 v[120:121], s[8:9], 0, v[2:3]
	v_lshl_add_u64 v[110:111], s[4:5], 0, v[2:3]
	v_cndmask_b32_e32 v119, v121, v119, vcc
	v_cndmask_b32_e32 v118, v120, v118, vcc
	v_lshl_add_u64 v[4:5], v[4:5], 0, s[6:7]
	global_load_dwordx4 v[86:89], v[118:119], off
	v_lshl_add_u64 v[2:3], v[2:3], 0, s[10:11]
	v_cmp_ge_u64_e32 vcc, s[16:17], v[4:5]
	s_and_b64 exec, exec, vcc
	s_cbranch_execz .Lmy_xc_ld_done
	s_mov_b64 s[34:35], exec
	v_cmp_gt_u64_e32 vcc, s[14:15], v[4:5]
	v_lshl_add_u64 v[118:119], s[36:37], 0, v[2:3]
	v_lshl_add_u64 v[120:121], s[8:9], 0, v[2:3]
	v_lshl_add_u64 v[112:113], s[4:5], 0, v[2:3]
	v_cndmask_b32_e32 v119, v121, v119, vcc
	v_cndmask_b32_e32 v118, v120, v118, vcc
	v_lshl_add_u64 v[4:5], v[4:5], 0, s[6:7]
	global_load_dwordx4 v[90:93], v[118:119], off
	v_lshl_add_u64 v[2:3], v[2:3], 0, s[10:11]
	v_cmp_ge_u64_e32 vcc, s[16:17], v[4:5]
	s_and_b64 exec, exec, vcc
	s_cbranch_execz .Lmy_xc_ld_done
	s_mov_b64 s[38:39], exec
	v_cmp_gt_u64_e32 vcc, s[14:15], v[4:5]
	v_lshl_add_u64 v[118:119], s[36:37], 0, v[2:3]
	v_lshl_add_u64 v[120:121], s[8:9], 0, v[2:3]
	v_lshl_add_u64 v[114:115], s[4:5], 0, v[2:3]
	v_cndmask_b32_e32 v119, v121, v119, vcc
	v_cndmask_b32_e32 v118, v120, v118, vcc
	v_lshl_add_u64 v[4:5], v[4:5], 0, s[6:7]
	global_load_dwordx4 v[94:97], v[118:119], off
	v_lshl_add_u64 v[2:3], v[2:3], 0, s[10:11]
	v_cmp_ge_u64_e32 vcc, s[16:17], v[4:5]
	s_and_b64 exec, exec, vcc
	s_cbranch_execz .Lmy_xc_ld_done
	s_mov_b64 s[42:43], exec
	v_cmp_gt_u64_e32 vcc, s[14:15], v[4:5]
	v_lshl_add_u64 v[118:119], s[36:37], 0, v[2:3]
	v_lshl_add_u64 v[120:121], s[8:9], 0, v[2:3]
	v_lshl_add_u64 v[116:117], s[4:5], 0, v[2:3]
	v_cndmask_b32_e32 v119, v121, v119, vcc
	v_cndmask_b32_e32 v118, v120, v118, vcc
	v_lshl_add_u64 v[4:5], v[4:5], 0, s[6:7]
	global_load_dwordx4 v[98:101], v[118:119], off
	v_lshl_add_u64 v[2:3], v[2:3], 0, s[10:11]
	v_cmp_ge_u64_e32 vcc, s[16:17], v[4:5]
	s_and_b64 exec, exec, vcc
.Lmy_xc_ld_done:
	s_mov_b64 s[12:13], exec
	s_waitcnt vmcnt(0)
	s_mov_b64 exec, s[24:25]
	global_store_dwordx4 v[102:103], v[70:73], off
	s_mov_b64 exec, s[26:27]
	s_cbranch_execz .Lmy_xc_st_done
	global_store_dwordx4 v[104:105], v[74:77], off
	s_mov_b64 exec, s[28:29]
	s_cbranch_execz .Lmy_xc_st_done
	global_store_dwordx4 v[106:107], v[78:81], off
	s_mov_b64 exec, s[30:31]
	s_cbranch_execz .Lmy_xc_st_done
	global_store_dwordx4 v[108:109], v[82:85], off
	s_mov_b64 exec, s[32:33]
	s_cbranch_execz .Lmy_xc_st_done
	global_store_dwordx4 v[110:111], v[86:89], off
	s_mov_b64 exec, s[34:35]
	s_cbranch_execz .Lmy_xc_st_done
	global_store_dwordx4 v[112:113], v[90:93], off
	s_mov_b64 exec, s[38:39]
	s_cbranch_execz .Lmy_xc_st_done
	global_store_dwordx4 v[114:115], v[94:97], off
	s_mov_b64 exec, s[42:43]
	s_cbranch_execz .Lmy_xc_st_done
	global_store_dwordx4 v[116:117], v[98:101], off
.Lmy_xc_st_done:
	s_mov_b64 exec, s[12:13]
	s_cbranch_execnz .LBB0_119
